# norm phases: parallelize serialized loads (split-K slice accumulation and modulation vectors)
# speedup vs baseline: 1.0222x; 1.0053x over previous
; template <bool L16, bool CPY, bool CI>
; __device__ __forceinline__ void norm_rows(Frame& F, const int ra, const int rb, const void* src, const int rbase, const float* g, const float* modl, const int off_sh, const int off_sc, const int nparts) {
;     ...
;         const int bidx = m < MLAT ? (m >> 12) : 4;
;         if (bidx != cb) { cb = bidx;
;             const f32x4* gp = (const f32x4*)g + F.lane; const f32x4* shp = (const f32x4*)(modl + (size_t)bidx * MODW + off_sh) + F.lane; const f32x4* scp = (const f32x4*)(modl + (size_t)bidx * MODW + off_sc) + F.lane;
; #pragma unroll
;             for (int j = 0; j < 8; ++j) { gm[j] = gp[64 * j] * (scp[64 * j] + 1.0f); sh[j] = shp[64 * j]; } }
.LBB0_140:
	s_min_i32 s4, s4, 0x4000
	s_ashr_i32 s13, s4, 12
	s_cmp_eq_u32 s13, s9
	s_cbranch_scc1 .LBB0_137
	s_mul_i32 s4, s13, 0xc000
	v_readlane_b32 s3, v255, 20
	s_mul_hi_i32 s5, s13, 0xc000
	s_add_u32 s4, s3, s4
	v_readlane_b32 s3, v255, 21
	s_addc_u32 s5, s3, s5
	v_lshl_add_u64 v[108:109], s[4:5], 0, v[2:3]
	v_add_co_u32_e32 v72, vcc, 0x2000, v108
	global_load_dwordx4 v[36:39], v[134:135], off
	s_nop 0
	v_addc_co_u32_e32 v73, vcc, 0, v109, vcc
	global_load_dwordx4 v[178:181], v[72:73], off
	s_mov_b64 s[18:19], 0x2000
	v_lshl_add_u64 v[96:97], v[108:109], 0, s[18:19]
	s_movk_i32 s3, 0x3000
	v_add_co_u32_e32 v128, vcc, s3, v108
	s_mov_b32 s9, s13
	s_nop 0
	v_addc_co_u32_e32 v129, vcc, 0, v109, vcc
	v_add_co_u32_e32 v158, vcc, s33, v108
	global_load_dwordx4 v[72:75], v2, s[4:5]
	global_load_dwordx4 v[76:79], v[134:135], off offset:1024
	global_load_dwordx4 v[182:185], v[96:97], off offset:1024
	v_addc_co_u32_e32 v159, vcc, 0, v109, vcc
	global_load_dwordx4 v[80:83], v2, s[4:5] offset:1024
	global_load_dwordx4 v[84:87], v[134:135], off offset:2048
	global_load_dwordx4 v[186:189], v[96:97], off offset:2048
	global_load_dwordx4 v[92:95], v2, s[4:5] offset:2048
	global_load_dwordx4 v[88:91], v[134:135], off offset:3072
	s_nop 0
	global_load_dwordx4 v[190:193], v[96:97], off offset:3072
	global_load_dwordx4 v[96:99], v2, s[4:5] offset:3072
	global_load_dwordx4 v[100:103], v[136:137], off
	global_load_dwordx4 v[194:197], v[128:129], off
	global_load_dwordx4 v[104:107], v[158:159], off
	global_load_dwordx4 v[108:111], v[138:139], off
	global_load_dwordx4 v[198:201], v[128:129], off offset:1024
	global_load_dwordx4 v[112:115], v[158:159], off offset:1024
	global_load_dwordx4 v[116:119], v[140:141], off
	global_load_dwordx4 v[202:205], v[128:129], off offset:2048
	global_load_dwordx4 v[120:123], v[158:159], off offset:2048
	global_load_dwordx4 v[124:127], v[142:143], off
	s_nop 0
	global_load_dwordx4 v[206:209], v[128:129], off offset:3072
	global_load_dwordx4 v[128:131], v[158:159], off offset:3072
	s_waitcnt vmcnt(0)
	v_pk_add_f32 v[180:181], v[180:181], 1.0 op_sel_hi:[1,0]
	v_pk_add_f32 v[178:179], v[178:179], 1.0 op_sel_hi:[1,0]
	v_pk_mul_f32 v[38:39], v[38:39], v[180:181]
	v_pk_mul_f32 v[36:37], v[36:37], v[178:179]
	v_pk_add_f32 v[184:185], v[184:185], 1.0 op_sel_hi:[1,0]
	v_pk_add_f32 v[182:183], v[182:183], 1.0 op_sel_hi:[1,0]
	v_pk_mul_f32 v[78:79], v[78:79], v[184:185]
	v_pk_mul_f32 v[76:77], v[76:77], v[182:183]
	v_pk_add_f32 v[188:189], v[188:189], 1.0 op_sel_hi:[1,0]
	v_pk_add_f32 v[186:187], v[186:187], 1.0 op_sel_hi:[1,0]
	v_pk_mul_f32 v[86:87], v[86:87], v[188:189]
	v_pk_mul_f32 v[84:85], v[84:85], v[186:187]
	v_pk_add_f32 v[192:193], v[192:193], 1.0 op_sel_hi:[1,0]
	v_pk_add_f32 v[190:191], v[190:191], 1.0 op_sel_hi:[1,0]
	v_pk_mul_f32 v[90:91], v[90:91], v[192:193]
	v_pk_mul_f32 v[88:89], v[88:89], v[190:191]
	v_pk_add_f32 v[196:197], v[196:197], 1.0 op_sel_hi:[1,0]
	v_pk_add_f32 v[194:195], v[194:195], 1.0 op_sel_hi:[1,0]
	v_pk_mul_f32 v[102:103], v[102:103], v[196:197]
	v_pk_mul_f32 v[100:101], v[100:101], v[194:195]
	v_pk_add_f32 v[200:201], v[200:201], 1.0 op_sel_hi:[1,0]
	v_pk_add_f32 v[198:199], v[198:199], 1.0 op_sel_hi:[1,0]
	v_pk_mul_f32 v[110:111], v[110:111], v[200:201]
	v_pk_mul_f32 v[108:109], v[108:109], v[198:199]
	v_pk_add_f32 v[204:205], v[204:205], 1.0 op_sel_hi:[1,0]
	v_pk_add_f32 v[202:203], v[202:203], 1.0 op_sel_hi:[1,0]
	v_pk_mul_f32 v[118:119], v[118:119], v[204:205]
	v_pk_mul_f32 v[116:117], v[116:117], v[202:203]
	v_pk_add_f32 v[208:209], v[208:209], 1.0 op_sel_hi:[1,0]
	v_pk_add_f32 v[206:207], v[206:207], 1.0 op_sel_hi:[1,0]
	v_pk_mul_f32 v[126:127], v[126:127], v[208:209]
	v_pk_mul_f32 v[124:125], v[124:125], v[206:207]
	s_branch .LBB0_137

; template <bool L16, bool CPY, bool CI>
; __device__ __forceinline__ void norm_rows(Frame& F, const int ra, const int rb, const void* src, const int rbase, const float* g, const float* modl, const int off_sh, const int off_sc, const int nparts) {
;     ...
;         const int bidx = m < MLAT ? (m >> 12) : 4;
;         if (bidx != cb) { cb = bidx;
;             const f32x4* gp = (const f32x4*)g + F.lane; const f32x4* shp = (const f32x4*)(modl + (size_t)bidx * MODW + off_sh) + F.lane; const f32x4* scp = (const f32x4*)(modl + (size_t)bidx * MODW + off_sc) + F.lane;
; #pragma unroll
;             for (int j = 0; j < 8; ++j) { gm[j] = gp[64 * j] * (scp[64 * j] + 1.0f); sh[j] = shp[64 * j]; } }
.LBB0_147:
	s_min_i32 s4, s4, 0x4000
	s_ashr_i32 s13, s4, 12
	s_cmp_eq_u32 s13, s9
	s_cbranch_scc1 .LBB0_144
	s_mul_i32 s4, s13, 0xc000
	v_readlane_b32 s3, v255, 20
	s_mul_hi_i32 s5, s13, 0xc000
	s_add_u32 s4, s3, s4
	v_readlane_b32 s3, v255, 21
	s_addc_u32 s5, s3, s5
	v_lshl_add_u64 v[108:109], s[4:5], 0, v[2:3]
	v_add_co_u32_e32 v72, vcc, 0x2000, v108
	global_load_dwordx4 v[36:39], v[136:137], off
	s_nop 0
	v_addc_co_u32_e32 v73, vcc, 0, v109, vcc
	global_load_dwordx4 v[178:181], v[72:73], off
	s_mov_b64 s[18:19], 0x2000
	v_lshl_add_u64 v[96:97], v[108:109], 0, s[18:19]
	s_movk_i32 s3, 0x3000
	v_add_co_u32_e32 v128, vcc, s3, v108
	s_mov_b32 s9, s13
	s_nop 0
	v_addc_co_u32_e32 v129, vcc, 0, v109, vcc
	v_add_co_u32_e32 v158, vcc, s33, v108
	global_load_dwordx4 v[72:75], v2, s[4:5]
	global_load_dwordx4 v[76:79], v[136:137], off offset:1024
	global_load_dwordx4 v[182:185], v[96:97], off offset:1024
	v_addc_co_u32_e32 v159, vcc, 0, v109, vcc
	global_load_dwordx4 v[80:83], v2, s[4:5] offset:1024
	global_load_dwordx4 v[84:87], v[136:137], off offset:2048
	global_load_dwordx4 v[186:189], v[96:97], off offset:2048
	global_load_dwordx4 v[92:95], v2, s[4:5] offset:2048
	global_load_dwordx4 v[88:91], v[136:137], off offset:3072
	s_nop 0
	global_load_dwordx4 v[190:193], v[96:97], off offset:3072
	global_load_dwordx4 v[96:99], v2, s[4:5] offset:3072
	global_load_dwordx4 v[100:103], v[138:139], off
	global_load_dwordx4 v[194:197], v[128:129], off
	global_load_dwordx4 v[104:107], v[158:159], off
	global_load_dwordx4 v[108:111], v[140:141], off
	global_load_dwordx4 v[198:201], v[128:129], off offset:1024
	global_load_dwordx4 v[112:115], v[158:159], off offset:1024
	global_load_dwordx4 v[116:119], v[142:143], off
	global_load_dwordx4 v[202:205], v[128:129], off offset:2048
	global_load_dwordx4 v[120:123], v[158:159], off offset:2048
	global_load_dwordx4 v[124:127], v[144:145], off
	s_nop 0
	global_load_dwordx4 v[206:209], v[128:129], off offset:3072
	global_load_dwordx4 v[128:131], v[158:159], off offset:3072
	s_waitcnt vmcnt(0)
	v_pk_add_f32 v[180:181], v[180:181], 1.0 op_sel_hi:[1,0]
	v_pk_add_f32 v[178:179], v[178:179], 1.0 op_sel_hi:[1,0]
	v_pk_mul_f32 v[38:39], v[38:39], v[180:181]
	v_pk_mul_f32 v[36:37], v[36:37], v[178:179]
	v_pk_add_f32 v[184:185], v[184:185], 1.0 op_sel_hi:[1,0]
	v_pk_add_f32 v[182:183], v[182:183], 1.0 op_sel_hi:[1,0]
	v_pk_mul_f32 v[78:79], v[78:79], v[184:185]
	v_pk_mul_f32 v[76:77], v[76:77], v[182:183]
	v_pk_add_f32 v[188:189], v[188:189], 1.0 op_sel_hi:[1,0]
	v_pk_add_f32 v[186:187], v[186:187], 1.0 op_sel_hi:[1,0]
	v_pk_mul_f32 v[86:87], v[86:87], v[188:189]
	v_pk_mul_f32 v[84:85], v[84:85], v[186:187]
	v_pk_add_f32 v[192:193], v[192:193], 1.0 op_sel_hi:[1,0]
	v_pk_add_f32 v[190:191], v[190:191], 1.0 op_sel_hi:[1,0]
	v_pk_mul_f32 v[90:91], v[90:91], v[192:193]
	v_pk_mul_f32 v[88:89], v[88:89], v[190:191]
	v_pk_add_f32 v[196:197], v[196:197], 1.0 op_sel_hi:[1,0]
	v_pk_add_f32 v[194:195], v[194:195], 1.0 op_sel_hi:[1,0]
	v_pk_mul_f32 v[102:103], v[102:103], v[196:197]
	v_pk_mul_f32 v[100:101], v[100:101], v[194:195]
	v_pk_add_f32 v[200:201], v[200:201], 1.0 op_sel_hi:[1,0]
	v_pk_add_f32 v[198:199], v[198:199], 1.0 op_sel_hi:[1,0]
	v_pk_mul_f32 v[110:111], v[110:111], v[200:201]
	v_pk_mul_f32 v[108:109], v[108:109], v[198:199]
	v_pk_add_f32 v[204:205], v[204:205], 1.0 op_sel_hi:[1,0]
	v_pk_add_f32 v[202:203], v[202:203], 1.0 op_sel_hi:[1,0]
	v_pk_mul_f32 v[118:119], v[118:119], v[204:205]
	v_pk_mul_f32 v[116:117], v[116:117], v[202:203]
	v_pk_add_f32 v[208:209], v[208:209], 1.0 op_sel_hi:[1,0]
	v_pk_add_f32 v[206:207], v[206:207], 1.0 op_sel_hi:[1,0]
	v_pk_mul_f32 v[126:127], v[126:127], v[208:209]
	v_pk_mul_f32 v[124:125], v[124:125], v[206:207]
	s_branch .LBB0_144

; template <bool L16, bool CPY, bool CI>
; __device__ __forceinline__ void norm_rows(Frame& F, const int ra, const int rb, const void* src, const int rbase, const float* g, const float* modl, const int off_sh, const int off_sc, const int nparts) {
;     ...
;         const int bidx = m < MLAT ? (m >> 12) : 4;
;         if (bidx != cb) { cb = bidx;
;             const f32x4* gp = (const f32x4*)g + F.lane; const f32x4* shp = (const f32x4*)(modl + (size_t)bidx * MODW + off_sh) + F.lane; const f32x4* scp = (const f32x4*)(modl + (size_t)bidx * MODW + off_sc) + F.lane;
; #pragma unroll
;             for (int j = 0; j < 8; ++j) { gm[j] = gp[64 * j] * (scp[64 * j] + 1.0f); sh[j] = shp[64 * j]; } }
.LBB0_158:
	s_min_i32 s4, s50, 0x4000
	s_ashr_i32 s9, s4, 12
	s_cmp_eq_u32 s9, s13
	s_cbranch_scc1 .LBB0_155
	s_mul_i32 s4, s9, 0xc000
	v_readlane_b32 s3, v255, 20
	s_mul_hi_i32 s5, s9, 0xc000
	s_add_u32 s4, s3, s4
	v_readlane_b32 s3, v255, 21
	s_addc_u32 s5, s3, s5
	v_lshl_add_u64 v[44:45], s[4:5], 0, v[2:3]
	v_add_co_u32_e32 v8, vcc, 0x2000, v44
	global_load_dwordx4 v[4:7], v[70:71], off
	s_nop 0
	v_addc_co_u32_e32 v9, vcc, 0, v45, vcc
	global_load_dwordx4 v[178:181], v[8:9], off
	s_mov_b64 s[18:19], 0x2000
	v_lshl_add_u64 v[32:33], v[44:45], 0, s[18:19]
	s_movk_i32 s3, 0x3000
	v_add_co_u32_e32 v64, vcc, s3, v44
	s_mov_b32 s13, s9
	s_nop 0
	v_addc_co_u32_e32 v65, vcc, 0, v45, vcc
	v_add_co_u32_e32 v120, vcc, s33, v44
	global_load_dwordx4 v[8:11], v2, s[4:5]
	global_load_dwordx4 v[12:15], v[70:71], off offset:1024
	global_load_dwordx4 v[182:185], v[32:33], off offset:1024
	v_addc_co_u32_e32 v121, vcc, 0, v45, vcc
	global_load_dwordx4 v[16:19], v2, s[4:5] offset:1024
	global_load_dwordx4 v[20:23], v[70:71], off offset:2048
	global_load_dwordx4 v[186:189], v[32:33], off offset:2048
	global_load_dwordx4 v[28:31], v2, s[4:5] offset:2048
	global_load_dwordx4 v[24:27], v[70:71], off offset:3072
	s_nop 0
	global_load_dwordx4 v[190:193], v[32:33], off offset:3072
	global_load_dwordx4 v[32:35], v2, s[4:5] offset:3072
	global_load_dwordx4 v[36:39], v[72:73], off
	global_load_dwordx4 v[194:197], v[64:65], off
	global_load_dwordx4 v[40:43], v[120:121], off
	global_load_dwordx4 v[44:47], v[74:75], off
	global_load_dwordx4 v[198:201], v[64:65], off offset:1024
	global_load_dwordx4 v[48:51], v[120:121], off offset:1024
	global_load_dwordx4 v[52:55], v[76:77], off
	global_load_dwordx4 v[202:205], v[64:65], off offset:2048
	global_load_dwordx4 v[56:59], v[120:121], off offset:2048
	global_load_dwordx4 v[60:63], v[78:79], off
	s_nop 0
	global_load_dwordx4 v[206:209], v[64:65], off offset:3072
	global_load_dwordx4 v[64:67], v[120:121], off offset:3072
	s_waitcnt vmcnt(0)
	v_pk_add_f32 v[180:181], v[180:181], 1.0 op_sel_hi:[1,0]
	v_pk_add_f32 v[178:179], v[178:179], 1.0 op_sel_hi:[1,0]
	v_pk_mul_f32 v[6:7], v[6:7], v[180:181]
	v_pk_mul_f32 v[4:5], v[4:5], v[178:179]
	v_pk_add_f32 v[184:185], v[184:185], 1.0 op_sel_hi:[1,0]
	v_pk_add_f32 v[182:183], v[182:183], 1.0 op_sel_hi:[1,0]
	v_pk_mul_f32 v[14:15], v[14:15], v[184:185]
	v_pk_mul_f32 v[12:13], v[12:13], v[182:183]
	v_pk_add_f32 v[188:189], v[188:189], 1.0 op_sel_hi:[1,0]
	v_pk_add_f32 v[186:187], v[186:187], 1.0 op_sel_hi:[1,0]
	v_pk_mul_f32 v[22:23], v[22:23], v[188:189]
	v_pk_mul_f32 v[20:21], v[20:21], v[186:187]
	v_pk_add_f32 v[192:193], v[192:193], 1.0 op_sel_hi:[1,0]
	v_pk_add_f32 v[190:191], v[190:191], 1.0 op_sel_hi:[1,0]
	v_pk_mul_f32 v[26:27], v[26:27], v[192:193]
	v_pk_mul_f32 v[24:25], v[24:25], v[190:191]
	v_pk_add_f32 v[196:197], v[196:197], 1.0 op_sel_hi:[1,0]
	v_pk_add_f32 v[194:195], v[194:195], 1.0 op_sel_hi:[1,0]
	v_pk_mul_f32 v[38:39], v[38:39], v[196:197]
	v_pk_mul_f32 v[36:37], v[36:37], v[194:195]
	v_pk_add_f32 v[200:201], v[200:201], 1.0 op_sel_hi:[1,0]
	v_pk_add_f32 v[198:199], v[198:199], 1.0 op_sel_hi:[1,0]
	v_pk_mul_f32 v[46:47], v[46:47], v[200:201]
	v_pk_mul_f32 v[44:45], v[44:45], v[198:199]
	v_pk_add_f32 v[204:205], v[204:205], 1.0 op_sel_hi:[1,0]
	v_pk_add_f32 v[202:203], v[202:203], 1.0 op_sel_hi:[1,0]
	v_pk_mul_f32 v[54:55], v[54:55], v[204:205]
	v_pk_mul_f32 v[52:53], v[52:53], v[202:203]
	v_pk_add_f32 v[208:209], v[208:209], 1.0 op_sel_hi:[1,0]
	v_pk_add_f32 v[206:207], v[206:207], 1.0 op_sel_hi:[1,0]
	v_pk_mul_f32 v[62:63], v[62:63], v[208:209]
	v_pk_mul_f32 v[60:61], v[60:61], v[206:207]
	s_branch .LBB0_155

; template <bool L16, bool CPY, bool CI>
; __device__ __forceinline__ void norm_rows(Frame& F, const int ra, const int rb, const void* src, const int rbase, const float* g, const float* modl, const int off_sh, const int off_sc, const int nparts) {
;     ...
;         if constexpr (CI) {
;             for (int k = 0; k < nparts; ++k) { const f32x4* pp = (const f32x4*)((const float*)(F.ws + WS_PART) + ((size_t)k * MCTX + (size_t)(m - rbase)) * D) + F.lane;
; #pragma unroll
;                 for (int j = 0; j < 8; ++j) v[j] = v[j] + pp[64 * j]; }
.LBB0_162:
	s_ashr_i32 s43, s42, 31
	s_lshl_b64 s[4:5], s[42:43], 13
	v_lshl_add_u64 v[152:153], v[136:137], 0, s[4:5]
	s_add_i32 s42, s42, 1
	s_cmp_ge_i32 s8, s10
	s_mov_b32 s1, 0x1000
	v_add_co_u32_e32 v162, vcc, s1, v152
	s_nop 1
	v_addc_co_u32_e32 v163, vcc, 0, v153, vcc
	s_mov_b32 s1, 0x800000
	v_add_co_u32_e32 v164, vcc, s1, v152
	s_nop 1
	v_addc_co_u32_e32 v165, vcc, 0, v153, vcc
	s_mov_b32 s1, 0x801000
	v_add_co_u32_e32 v166, vcc, s1, v152
	s_nop 1
	v_addc_co_u32_e32 v167, vcc, 0, v153, vcc
	global_load_dwordx4 v[172:175], v[152:153], off
	global_load_dwordx4 v[176:179], v[152:153], off offset:1024
	global_load_dwordx4 v[180:183], v[152:153], off offset:2048
	global_load_dwordx4 v[184:187], v[152:153], off offset:3072
	global_load_dwordx4 v[188:191], v[162:163], off
	global_load_dwordx4 v[192:195], v[162:163], off offset:1024
	global_load_dwordx4 v[196:199], v[162:163], off offset:2048
	global_load_dwordx4 v[200:203], v[162:163], off offset:3072
	global_load_dwordx4 v[204:207], v[164:165], off
	global_load_dwordx4 v[208:211], v[164:165], off offset:1024
	global_load_dwordx4 v[212:215], v[164:165], off offset:2048
	global_load_dwordx4 v[216:219], v[164:165], off offset:3072
	global_load_dwordx4 v[220:223], v[166:167], off
	global_load_dwordx4 v[224:227], v[166:167], off offset:1024
	global_load_dwordx4 v[228:231], v[166:167], off offset:2048
	global_load_dwordx4 v[232:235], v[166:167], off offset:3072
	s_waitcnt vmcnt(0)
	v_pk_add_f32 v[130:131], v[130:131], v[174:175]
	v_pk_add_f32 v[128:129], v[128:129], v[172:173]
	v_pk_add_f32 v[126:127], v[126:127], v[178:179]
	v_pk_add_f32 v[124:125], v[124:125], v[176:177]
	v_pk_add_f32 v[122:123], v[122:123], v[182:183]
	v_pk_add_f32 v[120:121], v[120:121], v[180:181]
	v_pk_add_f32 v[118:119], v[118:119], v[186:187]
	v_pk_add_f32 v[116:117], v[116:117], v[184:185]
	v_pk_add_f32 v[106:107], v[106:107], v[190:191]
	v_pk_add_f32 v[104:105], v[104:105], v[188:189]
	v_pk_add_f32 v[110:111], v[110:111], v[194:195]
	v_pk_add_f32 v[108:109], v[108:109], v[192:193]
	v_pk_add_f32 v[114:115], v[114:115], v[198:199]
	v_pk_add_f32 v[112:113], v[112:113], v[196:197]
	v_pk_add_f32 v[102:103], v[102:103], v[202:203]
	v_pk_add_f32 v[100:101], v[100:101], v[200:201]
	v_pk_add_f32 v[130:131], v[130:131], v[206:207]
	v_pk_add_f32 v[128:129], v[128:129], v[204:205]
	v_pk_add_f32 v[126:127], v[126:127], v[210:211]
	v_pk_add_f32 v[124:125], v[124:125], v[208:209]
	v_pk_add_f32 v[122:123], v[122:123], v[214:215]
	v_pk_add_f32 v[120:121], v[120:121], v[212:213]
	v_pk_add_f32 v[118:119], v[118:119], v[218:219]
	v_pk_add_f32 v[116:117], v[116:117], v[216:217]
	v_pk_add_f32 v[106:107], v[106:107], v[222:223]
	v_pk_add_f32 v[104:105], v[104:105], v[220:221]
	v_pk_add_f32 v[110:111], v[110:111], v[226:227]
	v_pk_add_f32 v[108:109], v[108:109], v[224:225]
	v_pk_add_f32 v[114:115], v[114:115], v[230:231]
	v_pk_add_f32 v[112:113], v[112:113], v[228:229]
	v_pk_add_f32 v[102:103], v[102:103], v[234:235]
	v_pk_add_f32 v[100:101], v[100:101], v[232:233]
	s_mov_b32 s1, 0x1000000
	v_add_co_u32_e32 v162, vcc, s1, v152
	s_nop 1
	v_addc_co_u32_e32 v163, vcc, 0, v153, vcc
	s_mov_b32 s1, 0x1001000
	v_add_co_u32_e32 v164, vcc, s1, v152
	s_nop 1
	v_addc_co_u32_e32 v165, vcc, 0, v153, vcc
	s_mov_b32 s1, 0x1800000
	v_add_co_u32_e32 v166, vcc, s1, v152
	s_nop 1
	v_addc_co_u32_e32 v167, vcc, 0, v153, vcc
	s_mov_b32 s1, 0x1801000
	v_add_co_u32_e32 v168, vcc, s1, v152
	s_nop 1
	v_addc_co_u32_e32 v169, vcc, 0, v153, vcc
	global_load_dwordx4 v[172:175], v[162:163], off
	global_load_dwordx4 v[176:179], v[162:163], off offset:1024
	global_load_dwordx4 v[180:183], v[162:163], off offset:2048
	global_load_dwordx4 v[184:187], v[162:163], off offset:3072
	global_load_dwordx4 v[188:191], v[164:165], off
	global_load_dwordx4 v[192:195], v[164:165], off offset:1024
	global_load_dwordx4 v[196:199], v[164:165], off offset:2048
	global_load_dwordx4 v[200:203], v[164:165], off offset:3072
	global_load_dwordx4 v[204:207], v[166:167], off
	global_load_dwordx4 v[208:211], v[166:167], off offset:1024
	global_load_dwordx4 v[212:215], v[166:167], off offset:2048
	global_load_dwordx4 v[216:219], v[166:167], off offset:3072
	global_load_dwordx4 v[220:223], v[168:169], off
	global_load_dwordx4 v[224:227], v[168:169], off offset:1024
	global_load_dwordx4 v[228:231], v[168:169], off offset:2048
	global_load_dwordx4 v[232:235], v[168:169], off offset:3072
	s_waitcnt vmcnt(0)
; template <bool L16, bool CPY, bool CI>
; __device__ __forceinline__ void norm_rows(Frame& F, const int ra, const int rb, const void* src, const int rbase, const float* g, const float* modl, const int off_sh, const int off_sc, const int nparts) {
;     ...
;             for (int k = 0; k < nparts; ++k) { const f32x4* pp = (const f32x4*)((const float*)(F.ws + WS_PART) + ((size_t)k * MCTX + (size_t)(m - rbase)) * D) + F.lane;
; #pragma unroll
;                 for (int j = 0; j < 8; ++j) v[j] = v[j] + pp[64 * j]; }
;             f32x4* xw = (f32x4*)((float*)(F.ws + WS_XR) + (size_t)m * D) + F.lane;
; #pragma unroll
;             for (int j = 0; j < 8; ++j) xw[64 * j] = v[j]; }
;         float s = 0.f;
; #pragma unroll
;         for (int j = 0; j < 8; ++j) s += (v[j].x * v[j].x + v[j].y * v[j].y) + (v[j].z * v[j].z + v[j].w * v[j].w);
;         const float r = 1.0f / sqrtf(wave_sum(s) * (1.0f / D) + EPS);
;         v2u* o8 = (v2u*)(H + (size_t)m * D) + F.lane;
	v_pk_add_f32 v[130:131], v[130:131], v[174:175]
	v_pk_add_f32 v[128:129], v[128:129], v[172:173]
	v_pk_add_f32 v[126:127], v[126:127], v[178:179]
	v_pk_add_f32 v[124:125], v[124:125], v[176:177]
	v_pk_add_f32 v[122:123], v[122:123], v[182:183]
	v_pk_add_f32 v[120:121], v[120:121], v[180:181]
	v_pk_add_f32 v[118:119], v[118:119], v[186:187]
	v_pk_add_f32 v[116:117], v[116:117], v[184:185]
	v_pk_add_f32 v[106:107], v[106:107], v[190:191]
	v_pk_add_f32 v[104:105], v[104:105], v[188:189]
	v_pk_add_f32 v[110:111], v[110:111], v[194:195]
	v_pk_add_f32 v[108:109], v[108:109], v[192:193]
	v_pk_add_f32 v[114:115], v[114:115], v[198:199]
	v_pk_add_f32 v[112:113], v[112:113], v[196:197]
	v_pk_add_f32 v[102:103], v[102:103], v[202:203]
	v_pk_add_f32 v[100:101], v[100:101], v[200:201]
	v_pk_add_f32 v[174:175], v[130:131], v[206:207]
	v_pk_add_f32 v[172:173], v[128:129], v[204:205]
	v_pk_add_f32 v[178:179], v[126:127], v[210:211]
	v_pk_add_f32 v[176:177], v[124:125], v[208:209]
	v_pk_add_f32 v[182:183], v[122:123], v[214:215]
	v_pk_add_f32 v[180:181], v[120:121], v[212:213]
	v_pk_add_f32 v[186:187], v[118:119], v[218:219]
	v_pk_add_f32 v[184:185], v[116:117], v[216:217]
	v_pk_add_f32 v[190:191], v[106:107], v[222:223]
	v_pk_add_f32 v[188:189], v[104:105], v[220:221]
	v_pk_add_f32 v[194:195], v[110:111], v[226:227]
	v_pk_add_f32 v[192:193], v[108:109], v[224:225]
	v_pk_add_f32 v[198:199], v[114:115], v[230:231]
	v_pk_add_f32 v[196:197], v[112:113], v[228:229]
	v_pk_add_f32 v[202:203], v[102:103], v[234:235]
	v_pk_add_f32 v[200:201], v[100:101], v[232:233]
	v_mov_b64_e32 v[100:101], v[172:173]
	v_mov_b64_e32 v[102:103], v[174:175]
	v_mov_b64_e32 v[108:109], v[176:177]
	v_mov_b64_e32 v[110:111], v[178:179]
	v_mov_b64_e32 v[104:105], v[180:181]
	v_mov_b64_e32 v[106:107], v[182:183]
	v_mov_b64_e32 v[112:113], v[184:185]
	v_mov_b64_e32 v[114:115], v[186:187]
	v_mov_b64_e32 v[120:121], v[188:189]
	v_mov_b64_e32 v[122:123], v[190:191]
	v_mov_b64_e32 v[116:117], v[192:193]
	v_mov_b64_e32 v[118:119], v[194:195]
	v_mov_b64_e32 v[124:125], v[196:197]
	v_mov_b64_e32 v[126:127], v[198:199]
	v_mov_b64_e32 v[128:129], v[200:201]
	v_mov_b64_e32 v[130:131], v[202:203]
	v_mul_f32_e32 v161, v120, v120
	s_mov_b32 s1, 0x15200000
	v_lshl_add_u64 v[132:133], s[38:39], 0, v[148:149]
	v_add_co_u32_e32 v152, vcc, s1, v132
	s_mov_b32 s1, 0x15201000
	s_nop 0
	v_addc_co_u32_e32 v153, vcc, 0, v133, vcc
	v_add_co_u32_e32 v132, vcc, s1, v132
	v_mov_b32_e32 v162, v103
	s_nop 0
	v_addc_co_u32_e32 v133, vcc, 0, v133, vcc
	global_store_dwordx4 v[132:133], v[100:103], off offset:-4096
	global_store_dwordx4 v[152:153], v[108:111], off offset:1024
	global_store_dwordx4 v[152:153], v[104:107], off offset:2048
	global_store_dwordx4 v[152:153], v[112:115], off offset:3072
	global_store_dwordx4 v[132:133], v[120:123], off
	global_store_dwordx4 v[132:133], v[116:119], off offset:1024
	global_store_dwordx4 v[132:133], v[124:127], off offset:2048
	global_store_dwordx4 v[132:133], v[128:131], off offset:3072
	v_mov_b32_e32 v152, v101
	v_mov_b32_e32 v153, v109
	v_mov_b32_e32 v132, v100
	v_mov_b32_e32 v133, v108
	v_pk_mul_f32 v[152:153], v[152:153], v[152:153]
	v_mov_b32_e32 v163, v111
	v_pk_fma_f32 v[132:133], v[132:133], v[132:133], v[152:153]
	v_mov_b32_e32 v152, v102
	v_mov_b32_e32 v153, v110
	v_pk_mul_f32 v[162:163], v[162:163], v[162:163]
	s_mov_b32 s1, 0xf800000
	v_pk_fma_f32 v[152:153], v[152:153], v[152:153], v[162:163]
	v_pk_mul_f32 v[162:163], v[104:105], v[104:105]
	v_pk_add_f32 v[132:133], v[132:133], v[152:153]
	v_pk_mul_f32 v[152:153], v[106:107], v[106:107]
	v_pk_add_f32 v[132:133], v[132:133], v[132:133] op_sel:[0,1] op_sel_hi:[1,0]
	v_pk_mov_b32 v[164:165], v[162:163], v[152:153] op_sel:[1,0]
	v_mov_b32_e32 v163, v153
	v_pk_add_f32 v[152:153], v[164:165], v[162:163]
	v_mul_f32_e32 v162, v121, v121
	v_pk_add_f32 v[152:153], v[152:153], v[152:153] op_sel:[0,1] op_sel_hi:[1,0]
	v_mov_b32_e32 v133, v161
	v_mov_b32_e32 v153, v162
	v_pk_add_f32 v[132:133], v[132:133], v[152:153]
	v_mul_f32_e32 v152, v113, v113
	v_mul_f32_e32 v163, v122, v122
	v_pk_fma_f32 v[152:153], v[112:113], v[112:113], v[152:153] op_sel_hi:[1,1,0]
	v_mul_f32_e32 v162, v115, v115
	v_mul_f32_e32 v164, v123, v123
	v_mov_b32_e32 v153, v163
	v_pk_fma_f32 v[162:163], v[114:115], v[114:115], v[162:163] op_sel_hi:[1,1,0]
	v_mul_f32_e32 v161, v128, v128
	v_mov_b32_e32 v163, v164
	v_pk_add_f32 v[152:153], v[152:153], v[162:163]
	v_pk_mul_f32 v[162:163], v[116:117], v[116:117]
	v_pk_add_f32 v[132:133], v[132:133], v[152:153]
	v_pk_mul_f32 v[152:153], v[118:119], v[118:119]
	v_pk_add_f32 v[132:133], v[132:133], v[132:133] op_sel:[0,1] op_sel_hi:[1,0]
	v_pk_mov_b32 v[164:165], v[162:163], v[152:153] op_sel:[1,0]
	v_mov_b32_e32 v163, v153
	v_pk_add_f32 v[152:153], v[164:165], v[162:163]
	v_mul_f32_e32 v162, v129, v129
	v_pk_add_f32 v[152:153], v[152:153], v[152:153] op_sel:[0,1] op_sel_hi:[1,0]
	v_mov_b32_e32 v133, v161
	v_mov_b32_e32 v153, v162
	v_pk_add_f32 v[132:133], v[132:133], v[152:153]
	v_mul_f32_e32 v152, v125, v125
	v_mul_f32_e32 v163, v130, v130
	v_pk_fma_f32 v[152:153], v[124:125], v[124:125], v[152:153] op_sel_hi:[1,1,0]
	v_mul_f32_e32 v162, v127, v127
	v_mul_f32_e32 v164, v131, v131
	v_mov_b32_e32 v153, v163
	v_pk_fma_f32 v[162:163], v[126:127], v[126:127], v[162:163] op_sel_hi:[1,1,0]
	s_nop 0
	v_mov_b32_e32 v163, v164
	v_pk_add_f32 v[152:153], v[152:153], v[162:163]
	s_nop 0
	v_pk_add_f32 v[132:133], v[132:133], v[152:153]
	s_nop 0
	v_add_f32_e32 v132, v132, v133
	ds_bpermute_b32 v133, v155, v132
	s_waitcnt lgkmcnt(0)
	v_add_f32_e32 v132, v132, v133
	ds_bpermute_b32 v133, v156, v132
	s_waitcnt lgkmcnt(0)
; __device__ __forceinline__ unsigned pk_h2(float lo, float hi) { f16x2 p; p.x = (_Float16)__builtin_amdgcn_fmed3f(lo, -65504.0f, 65504.0f); p.y = (_Float16)__builtin_amdgcn_fmed3f(hi, -65504.0f, 65504.0f); return __builtin_bit_cast(unsigned, p); }
; __device__ __forceinline__ unsigned pk2h(float lo, float hi) { return pg8::cvt_pk_bf16(lo, hi); }
; template <bool L16, bool CPY, bool CI>
; __device__ __forceinline__ void norm_rows(Frame& F, const int ra, const int rb, const void* src, const int rbase, const float* g, const float* modl, const int off_sh, const int off_sc, const int nparts) {
;     ...
;         for (int j = 0; j < 8; ++j) s += (v[j].x * v[j].x + v[j].y * v[j].y) + (v[j].z * v[j].z + v[j].w * v[j].w);
;         const float r = 1.0f / sqrtf(wave_sum(s) * (1.0f / D) + EPS);
;         v2u* o8 = (v2u*)(H + (size_t)m * D) + F.lane;
; #pragma unroll
;         for (int j = 0; j < 8; ++j) { const f32x4 y = v[j] * r * gm[j] + sh[j]; v2u ww; ww.x = pk2h(y.x, y.y); ww.y = pk2h(y.z, y.w); o8[64 * j] = ww; }
;         if constexpr (CPY) { v2u* c8 = (v2u*)((bf16*)(F.ws + WS_X16) + (size_t)m * D) + F.lane;
; #pragma unroll
;             for (int j = 0; j < 8; ++j) { v2u ww; ww.x = pg8::pk_h2(v[j].x, v[j].y); ww.y = pg8::pk_h2(v[j].z, v[j].w); c8[64 * j] = ww; } }
;         if constexpr (L16) {
; #pragma unroll
;             for (int j = 0; j < 8; ++j) hv[j] = hw[j];
;         } else {
; #pragma unroll
;             for (int j = 0; j < 8; ++j) v[j] = w[j]; }
	v_add_f32_e32 v132, v132, v133
	ds_bpermute_b32 v133, v157, v132
	s_waitcnt lgkmcnt(0)
	v_add_f32_e32 v132, v132, v133
	ds_bpermute_b32 v133, v158, v132
	s_waitcnt lgkmcnt(0)
	v_add_f32_e32 v132, v132, v133
	ds_bpermute_b32 v133, v159, v132
	s_waitcnt lgkmcnt(0)
	v_add_f32_e32 v132, v132, v133
	ds_bpermute_b32 v133, v160, v132
	s_waitcnt lgkmcnt(0)
	v_add_f32_e32 v132, v132, v133
	v_fmamk_f32 v132, v132, 0x3a000000, v244
	v_cmp_gt_f32_e32 vcc, s1, v132
	v_mul_f32_e32 v133, 0x4f800000, v132
	s_mov_b32 s1, 0x1da00000
	v_cndmask_b32_e32 v132, v132, v133, vcc
	v_sqrt_f32_e32 v133, v132
	s_nop 0
	v_add_u32_e32 v152, -1, v133
	v_fma_f32 v153, -v152, v133, v132
	v_cmp_ge_f32_e64 s[4:5], 0, v153
	v_add_u32_e32 v153, 1, v133
	s_nop 0
	v_cndmask_b32_e64 v152, v133, v152, s[4:5]
	v_fma_f32 v133, -v153, v133, v132
	v_cmp_lt_f32_e64 s[4:5], 0, v133
	s_nop 1
	v_cndmask_b32_e64 v133, v152, v153, s[4:5]
	v_mul_f32_e32 v152, 0x37800000, v133
	v_cndmask_b32_e32 v133, v133, v152, vcc
	v_cmp_class_f32_e32 vcc, v132, v245
	s_nop 1
	v_cndmask_b32_e32 v132, v133, v132, vcc
	v_div_scale_f32 v133, s[4:5], v132, v132, 1.0
	v_rcp_f32_e32 v152, v133
	s_mov_b64 s[4:5], 0x2000
	v_lshl_add_u64 v[148:149], v[148:149], 0, s[4:5]
	s_mov_b64 s[4:5], 0x1000
	v_fma_f32 v153, -v133, v152, 1.0
	v_fmac_f32_e32 v152, v153, v152
	v_div_scale_f32 v153, vcc, 1.0, v132, 1.0
	v_mul_f32_e32 v161, v153, v152
	v_fma_f32 v162, -v133, v161, v153
	v_fmac_f32_e32 v161, v162, v152
	v_fma_f32 v133, -v133, v161, v153
	v_div_fmas_f32 v133, v133, v152, v161
	v_div_fixup_f32 v132, v133, v132, 1.0
	v_pk_mul_f32 v[100:101], v[100:101], v[132:133] op_sel_hi:[1,0]
	v_pk_mul_f32 v[102:103], v[102:103], v[132:133] op_sel_hi:[1,0]
	v_lshl_add_u64 v[152:153], s[38:39], 0, v[150:151]
	v_pk_fma_f32 v[102:103], v[6:7], v[102:103], v[42:43]
	v_pk_fma_f32 v[100:101], v[4:5], v[100:101], v[40:41]
	v_lshl_add_u64 v[150:151], v[150:151], 0, s[4:5]
	v_cvt_pk_bf16_f32 v100, v100, v101
	v_cvt_pk_bf16_f32 v101, v102, v103
	v_add_co_u32_e32 v102, vcc, s1, v152
	s_nop 1
	v_addc_co_u32_e32 v103, vcc, 0, v153, vcc
	global_store_dwordx2 v[102:103], v[100:101], off
	v_pk_mul_f32 v[100:101], v[108:109], v[132:133] op_sel_hi:[1,0]
	v_pk_mul_f32 v[108:109], v[110:111], v[132:133] op_sel_hi:[1,0]
	v_pk_fma_f32 v[100:101], v[44:45], v[100:101], v[48:49]
	v_pk_fma_f32 v[108:109], v[46:47], v[108:109], v[50:51]
	v_cvt_pk_bf16_f32 v100, v100, v101
	v_mov_b32_e32 v110, v34
	v_cvt_pk_bf16_f32 v101, v108, v109
	global_store_dwordx2 v[102:103], v[100:101], off offset:512
	v_pk_mul_f32 v[100:101], v[104:105], v[132:133] op_sel_hi:[1,0]
	v_pk_mul_f32 v[104:105], v[106:107], v[132:133] op_sel_hi:[1,0]
	v_pk_fma_f32 v[100:101], v[52:53], v[100:101], v[60:61]
	v_pk_fma_f32 v[104:105], v[54:55], v[104:105], v[62:63]
	v_cvt_pk_bf16_f32 v100, v100, v101
	v_mov_b32_e32 v106, v38
	v_cvt_pk_bf16_f32 v101, v104, v105
	global_store_dwordx2 v[102:103], v[100:101], off offset:1024
	v_pk_mul_f32 v[100:101], v[112:113], v[132:133] op_sel_hi:[1,0]
	v_pk_mul_f32 v[104:105], v[114:115], v[132:133] op_sel_hi:[1,0]
	v_pk_fma_f32 v[100:101], v[56:57], v[100:101], v[64:65]
	v_pk_fma_f32 v[104:105], v[58:59], v[104:105], v[66:67]
	v_cvt_pk_bf16_f32 v100, v100, v101
	v_mov_b32_e32 v107, v39
	v_cvt_pk_bf16_f32 v101, v104, v105
	global_store_dwordx2 v[102:103], v[100:101], off offset:1536
	v_pk_mul_f32 v[100:101], v[120:121], v[132:133] op_sel_hi:[1,0]
	v_pk_mul_f32 v[104:105], v[122:123], v[132:133] op_sel_hi:[1,0]
	v_pk_fma_f32 v[100:101], v[68:69], v[100:101], v[72:73]
	v_pk_fma_f32 v[104:105], v[70:71], v[104:105], v[74:75]
	v_cvt_pk_bf16_f32 v100, v100, v101
	v_mov_b32_e32 v120, v12
	v_cvt_pk_bf16_f32 v101, v104, v105
	global_store_dwordx2 v[102:103], v[100:101], off offset:2048
	v_pk_mul_f32 v[100:101], v[116:117], v[132:133] op_sel_hi:[1,0]
	v_pk_mul_f32 v[104:105], v[118:119], v[132:133] op_sel_hi:[1,0]
	v_pk_fma_f32 v[100:101], v[76:77], v[100:101], v[80:81]
	v_pk_fma_f32 v[104:105], v[78:79], v[104:105], v[82:83]
	v_cvt_pk_bf16_f32 v100, v100, v101
	v_mov_b32_e32 v121, v13
	v_cvt_pk_bf16_f32 v101, v104, v105
	global_store_dwordx2 v[102:103], v[100:101], off offset:2560
	v_pk_mul_f32 v[100:101], v[124:125], v[132:133] op_sel_hi:[1,0]
	v_pk_mul_f32 v[104:105], v[126:127], v[132:133] op_sel_hi:[1,0]
	v_pk_fma_f32 v[100:101], v[84:85], v[100:101], v[88:89]
	v_pk_fma_f32 v[104:105], v[86:87], v[104:105], v[90:91]
	v_cvt_pk_bf16_f32 v100, v100, v101
	v_mov_b32_e32 v124, v16
	v_cvt_pk_bf16_f32 v101, v104, v105
	global_store_dwordx2 v[102:103], v[100:101], off offset:3072
	v_pk_mul_f32 v[100:101], v[128:129], v[132:133] op_sel_hi:[1,0]
	v_pk_mul_f32 v[104:105], v[130:131], v[132:133] op_sel_hi:[1,0]
	v_pk_fma_f32 v[100:101], v[92:93], v[100:101], v[96:97]
	v_pk_fma_f32 v[104:105], v[94:95], v[104:105], v[98:99]
	v_cvt_pk_bf16_f32 v100, v100, v101
	v_mov_b32_e32 v128, v20
	v_cvt_pk_bf16_f32 v101, v104, v105
	global_store_dwordx2 v[102:103], v[100:101], off offset:3584
	v_mov_b64_e32 v[102:103], v[26:27]
	v_mov_b64_e32 v[100:101], v[24:25]
	v_mov_b32_e32 v129, v21
	v_mov_b32_e32 v130, v22
	v_mov_b32_e32 v131, v23
	v_mov_b32_e32 v125, v17
	v_mov_b32_e32 v126, v18
	v_mov_b32_e32 v127, v19
	v_mov_b32_e32 v122, v14
	v_mov_b32_e32 v123, v15
	v_mov_b32_e32 v116, v8
	v_mov_b32_e32 v117, v9
	v_mov_b32_e32 v118, v10
	v_mov_b32_e32 v119, v11
	v_mov_b32_e32 v104, v36
	v_mov_b32_e32 v105, v37
	v_mov_b32_e32 v108, v32
	v_mov_b32_e32 v109, v33
	v_mov_b32_e32 v111, v35
	v_mov_b32_e32 v112, v28
	v_mov_b32_e32 v113, v29
	v_mov_b32_e32 v114, v30
	v_mov_b32_e32 v115, v31
	s_cbranch_scc1 .LBB0_167

; template <bool L16, bool CPY, bool CI>
; __device__ __forceinline__ void norm_rows(Frame& F, const int ra, const int rb, const void* src, const int rbase, const float* g, const float* modl, const int off_sh, const int off_sc, const int nparts) {
;     ...
;         const int bidx = m < MLAT ? (m >> 12) : 4;
;         if (bidx != cb) { cb = bidx;
;             const f32x4* gp = (const f32x4*)g + F.lane; const f32x4* shp = (const f32x4*)(modl + (size_t)bidx * MODW + off_sh) + F.lane; const f32x4* scp = (const f32x4*)(modl + (size_t)bidx * MODW + off_sc) + F.lane;
; #pragma unroll
;             for (int j = 0; j < 8; ++j) { gm[j] = gp[64 * j] * (scp[64 * j] + 1.0f); sh[j] = shp[64 * j]; } }
.LBB0_165:
	s_add_i32 s1, s42, 0x4000
	s_min_i32 s1, s1, 0x4000
	s_ashr_i32 s4, s1, 12
	s_cmp_eq_u32 s4, s0
	s_cbranch_scc1 .LBB0_162
	s_mul_i32 s0, s4, 0xc000
	v_readlane_b32 s3, v255, 20
	s_mul_hi_i32 s1, s4, 0xc000
	s_add_u32 s0, s3, s0
	v_readlane_b32 s3, v255, 21
	s_addc_u32 s1, s3, s1
	v_lshl_add_u64 v[76:77], s[0:1], 0, v[2:3]
	v_add_co_u32_e32 v40, vcc, 0x2000, v76
	global_load_dwordx4 v[4:7], v[138:139], off
	s_nop 0
	v_addc_co_u32_e32 v41, vcc, 0, v77, vcc
	global_load_dwordx4 v[178:181], v[40:41], off
	s_mov_b64 s[12:13], 0x2000
	v_lshl_add_u64 v[64:65], v[76:77], 0, s[12:13]
	global_load_dwordx4 v[40:43], v2, s[0:1]
	global_load_dwordx4 v[44:47], v[138:139], off offset:1024
	global_load_dwordx4 v[182:185], v[64:65], off offset:1024
	global_load_dwordx4 v[48:51], v2, s[0:1] offset:1024
	global_load_dwordx4 v[52:55], v[138:139], off offset:2048
	global_load_dwordx4 v[186:189], v[64:65], off offset:2048
	global_load_dwordx4 v[60:63], v2, s[0:1] offset:2048
	global_load_dwordx4 v[56:59], v[138:139], off offset:3072
	s_nop 0
	global_load_dwordx4 v[190:193], v[64:65], off offset:3072
	global_load_dwordx4 v[64:67], v2, s[0:1] offset:3072
	global_load_dwordx4 v[68:71], v[140:141], off
	s_movk_i32 s0, 0x3000
	v_add_co_u32_e32 v96, vcc, s0, v76
	s_mov_b32 s0, s4
	s_nop 0
	v_addc_co_u32_e32 v97, vcc, 0, v77, vcc
	global_load_dwordx4 v[194:197], v[96:97], off
	v_add_co_u32_e32 v132, vcc, s33, v76
	s_nop 1
	v_addc_co_u32_e32 v133, vcc, 0, v77, vcc
	global_load_dwordx4 v[72:75], v[132:133], off
	global_load_dwordx4 v[76:79], v[142:143], off
	global_load_dwordx4 v[198:201], v[96:97], off offset:1024
	global_load_dwordx4 v[80:83], v[132:133], off offset:1024
	global_load_dwordx4 v[84:87], v[144:145], off
	global_load_dwordx4 v[202:205], v[96:97], off offset:2048
	global_load_dwordx4 v[88:91], v[132:133], off offset:2048
	global_load_dwordx4 v[92:95], v[146:147], off
	s_nop 0
	global_load_dwordx4 v[206:209], v[96:97], off offset:3072
	global_load_dwordx4 v[96:99], v[132:133], off offset:3072
	s_waitcnt vmcnt(0)
	v_pk_add_f32 v[180:181], v[180:181], 1.0 op_sel_hi:[1,0]
	v_pk_add_f32 v[178:179], v[178:179], 1.0 op_sel_hi:[1,0]
	v_pk_mul_f32 v[6:7], v[6:7], v[180:181]
	v_pk_mul_f32 v[4:5], v[4:5], v[178:179]
	v_pk_add_f32 v[184:185], v[184:185], 1.0 op_sel_hi:[1,0]
	v_pk_add_f32 v[182:183], v[182:183], 1.0 op_sel_hi:[1,0]
	v_pk_mul_f32 v[46:47], v[46:47], v[184:185]
	v_pk_mul_f32 v[44:45], v[44:45], v[182:183]
	v_pk_add_f32 v[188:189], v[188:189], 1.0 op_sel_hi:[1,0]
	v_pk_add_f32 v[186:187], v[186:187], 1.0 op_sel_hi:[1,0]
	v_pk_mul_f32 v[54:55], v[54:55], v[188:189]
	v_pk_mul_f32 v[52:53], v[52:53], v[186:187]
	v_pk_add_f32 v[192:193], v[192:193], 1.0 op_sel_hi:[1,0]
	v_pk_add_f32 v[190:191], v[190:191], 1.0 op_sel_hi:[1,0]
	v_pk_mul_f32 v[58:59], v[58:59], v[192:193]
	v_pk_mul_f32 v[56:57], v[56:57], v[190:191]
	v_pk_add_f32 v[196:197], v[196:197], 1.0 op_sel_hi:[1,0]
	v_pk_add_f32 v[194:195], v[194:195], 1.0 op_sel_hi:[1,0]
	v_pk_mul_f32 v[70:71], v[70:71], v[196:197]
	v_pk_mul_f32 v[68:69], v[68:69], v[194:195]
	v_pk_add_f32 v[200:201], v[200:201], 1.0 op_sel_hi:[1,0]
	v_pk_add_f32 v[198:199], v[198:199], 1.0 op_sel_hi:[1,0]
	v_pk_mul_f32 v[78:79], v[78:79], v[200:201]
	v_pk_mul_f32 v[76:77], v[76:77], v[198:199]
	v_pk_add_f32 v[204:205], v[204:205], 1.0 op_sel_hi:[1,0]
	v_pk_add_f32 v[202:203], v[202:203], 1.0 op_sel_hi:[1,0]
	v_pk_mul_f32 v[86:87], v[86:87], v[204:205]
	v_pk_mul_f32 v[84:85], v[84:85], v[202:203]
	v_pk_add_f32 v[208:209], v[208:209], 1.0 op_sel_hi:[1,0]
	v_pk_add_f32 v[206:207], v[206:207], 1.0 op_sel_hi:[1,0]
	v_pk_mul_f32 v[94:95], v[94:95], v[208:209]
	v_pk_mul_f32 v[92:93], v[92:93], v[206:207]
	s_branch .LBB0_162

; template <bool L16, bool CPY, bool CI>
; __device__ __forceinline__ void norm_rows(Frame& F, const int ra, const int rb, const void* src, const int rbase, const float* g, const float* modl, const int off_sh, const int off_sc, const int nparts) {
;     ...
;         const int bidx = m < MLAT ? (m >> 12) : 4;
;         if (bidx != cb) { cb = bidx;
;             const f32x4* gp = (const f32x4*)g + F.lane; const f32x4* shp = (const f32x4*)(modl + (size_t)bidx * MODW + off_sh) + F.lane; const f32x4* scp = (const f32x4*)(modl + (size_t)bidx * MODW + off_sc) + F.lane;
; #pragma unroll
;             for (int j = 0; j < 8; ++j) { gm[j] = gp[64 * j] * (scp[64 * j] + 1.0f); sh[j] = shp[64 * j]; } }
.LBB0_1160:
	s_min_i32 s4, s4, 0x4000
	s_ashr_i32 s4, s4, 12
	s_cmp_eq_u32 s4, s19
	s_cbranch_scc1 .LBB0_1157
	s_mul_i32 s15, s4, 0xc000
	v_readlane_b32 s3, v255, 20
	s_mul_hi_i32 s5, s4, 0xc000
	s_add_u32 s20, s3, s15
	v_readlane_b32 s3, v255, 21
	s_addc_u32 s21, s3, s5
	v_lshl_add_u64 v[40:41], s[20:21], 0, v[2:3]
	v_add_co_u32_e32 v8, vcc, 0x8000, v40
	global_load_dwordx4 v[4:7], v[72:73], off
	s_nop 0
	v_addc_co_u32_e32 v9, vcc, 0, v41, vcc
	global_load_dwordx4 v[164:167], v[8:9], off
	s_movk_i32 s3, 0x7000
	s_mov_b64 s[20:21], 0x6000
	v_add_co_u32_e32 v64, vcc, s3, v40
	v_lshl_add_u64 v[36:37], v[40:41], 0, s[20:21]
	s_mov_b64 s[20:21], 0x8000
	v_addc_co_u32_e32 v65, vcc, 0, v41, vcc
	v_lshl_add_u64 v[32:33], v[40:41], 0, s[20:21]
	s_mov_b32 s3, 0x9000
	v_add_co_u32_e32 v66, vcc, s3, v40
	s_mov_b32 s19, s4
	s_nop 0
	v_addc_co_u32_e32 v67, vcc, 0, v41, vcc
	global_load_dwordx4 v[8:11], v[64:65], off offset:-4096
	global_load_dwordx4 v[12:15], v[72:73], off offset:1024
	global_load_dwordx4 v[168:171], v[32:33], off offset:1024
	global_load_dwordx4 v[16:19], v[36:37], off offset:1024
	global_load_dwordx4 v[20:23], v[72:73], off offset:2048
	global_load_dwordx4 v[172:175], v[32:33], off offset:2048
	global_load_dwordx4 v[24:27], v[36:37], off offset:2048
	global_load_dwordx4 v[28:31], v[72:73], off offset:3072
	s_nop 0
	global_load_dwordx4 v[176:179], v[32:33], off offset:3072
	global_load_dwordx4 v[32:35], v[36:37], off offset:3072
	s_nop 0
	global_load_dwordx4 v[36:39], v[74:75], off
	global_load_dwordx4 v[180:183], v[66:67], off
	global_load_dwordx4 v[40:43], v[64:65], off
	global_load_dwordx4 v[44:47], v[78:79], off
	global_load_dwordx4 v[184:187], v[66:67], off offset:1024
	global_load_dwordx4 v[48:51], v[64:65], off offset:1024
	global_load_dwordx4 v[52:55], v[80:81], off
	global_load_dwordx4 v[188:191], v[66:67], off offset:2048
	global_load_dwordx4 v[56:59], v[64:65], off offset:2048
	global_load_dwordx4 v[60:63], v[82:83], off
	global_load_dwordx4 v[192:195], v[66:67], off offset:3072
	s_nop 0
	global_load_dwordx4 v[64:67], v[64:65], off offset:3072
	s_nop 0
	s_waitcnt vmcnt(0)
	v_pk_add_f32 v[166:167], v[166:167], 1.0 op_sel_hi:[1,0]
	v_pk_add_f32 v[164:165], v[164:165], 1.0 op_sel_hi:[1,0]
	v_pk_mul_f32 v[6:7], v[6:7], v[166:167]
	v_pk_mul_f32 v[4:5], v[4:5], v[164:165]
	v_pk_add_f32 v[170:171], v[170:171], 1.0 op_sel_hi:[1,0]
	v_pk_add_f32 v[168:169], v[168:169], 1.0 op_sel_hi:[1,0]
	v_pk_mul_f32 v[14:15], v[14:15], v[170:171]
	v_pk_mul_f32 v[12:13], v[12:13], v[168:169]
	v_pk_add_f32 v[174:175], v[174:175], 1.0 op_sel_hi:[1,0]
	v_pk_add_f32 v[172:173], v[172:173], 1.0 op_sel_hi:[1,0]
	v_pk_mul_f32 v[22:23], v[22:23], v[174:175]
	v_pk_mul_f32 v[20:21], v[20:21], v[172:173]
	v_pk_add_f32 v[178:179], v[178:179], 1.0 op_sel_hi:[1,0]
	v_pk_add_f32 v[176:177], v[176:177], 1.0 op_sel_hi:[1,0]
	v_pk_mul_f32 v[30:31], v[30:31], v[178:179]
	v_pk_mul_f32 v[28:29], v[28:29], v[176:177]
	v_pk_add_f32 v[182:183], v[182:183], 1.0 op_sel_hi:[1,0]
	v_pk_add_f32 v[180:181], v[180:181], 1.0 op_sel_hi:[1,0]
	v_pk_mul_f32 v[38:39], v[38:39], v[182:183]
	v_pk_mul_f32 v[36:37], v[36:37], v[180:181]
	v_pk_add_f32 v[186:187], v[186:187], 1.0 op_sel_hi:[1,0]
	v_pk_add_f32 v[184:185], v[184:185], 1.0 op_sel_hi:[1,0]
	v_pk_mul_f32 v[46:47], v[46:47], v[186:187]
	v_pk_mul_f32 v[44:45], v[44:45], v[184:185]
	v_pk_add_f32 v[190:191], v[190:191], 1.0 op_sel_hi:[1,0]
	v_pk_add_f32 v[188:189], v[188:189], 1.0 op_sel_hi:[1,0]
	v_pk_mul_f32 v[54:55], v[54:55], v[190:191]
	v_pk_mul_f32 v[52:53], v[52:53], v[188:189]
	v_pk_add_f32 v[194:195], v[194:195], 1.0 op_sel_hi:[1,0]
	v_pk_add_f32 v[192:193], v[192:193], 1.0 op_sel_hi:[1,0]
	v_pk_mul_f32 v[62:63], v[62:63], v[194:195]
	v_pk_mul_f32 v[60:61], v[60:61], v[192:193]
	s_branch .LBB0_1157

; template <bool L16, bool CPY, bool CI>
; __device__ __forceinline__ void norm_rows(Frame& F, const int ra, const int rb, const void* src, const int rbase, const float* g, const float* modl, const int off_sh, const int off_sc, const int nparts) {
;     ...
;         const int bidx = m < MLAT ? (m >> 12) : 4;
;         if (bidx != cb) { cb = bidx;
;             const f32x4* gp = (const f32x4*)g + F.lane; const f32x4* shp = (const f32x4*)(modl + (size_t)bidx * MODW + off_sh) + F.lane; const f32x4* scp = (const f32x4*)(modl + (size_t)bidx * MODW + off_sc) + F.lane;
; #pragma unroll
;             for (int j = 0; j < 8; ++j) { gm[j] = gp[64 * j] * (scp[64 * j] + 1.0f); sh[j] = shp[64 * j]; } }
.LBB0_1166:
	s_min_i32 s1, s6, 0x4000
	s_ashr_i32 s1, s1, 12
	s_cmp_eq_u32 s1, s18
	s_cbranch_scc1 .LBB0_1168
	s_mul_i32 s4, s1, 0xc000
	v_readlane_b32 s3, v255, 20
	s_mul_hi_i32 s5, s1, 0xc000
	s_add_u32 s4, s3, s4
	v_readlane_b32 s3, v255, 21
	s_addc_u32 s5, s3, s5
	v_lshl_add_u64 v[104:105], s[4:5], 0, v[2:3]
	v_add_co_u32_e32 v28, vcc, 0x8000, v104
	global_load_dwordx4 v[4:7], v[138:139], off
	s_nop 0
	v_addc_co_u32_e32 v29, vcc, 0, v105, vcc
	global_load_dwordx4 v[164:167], v[28:29], off
	s_movk_i32 s3, 0x7000
	s_mov_b64 s[4:5], 0x6000
	v_add_co_u32_e32 v128, vcc, s3, v104
	v_lshl_add_u64 v[100:101], v[104:105], 0, s[4:5]
	s_mov_b64 s[4:5], 0x8000
	v_addc_co_u32_e32 v129, vcc, 0, v105, vcc
	v_lshl_add_u64 v[96:97], v[104:105], 0, s[4:5]
	s_mov_b32 s3, 0x9000
	v_add_co_u32_e32 v130, vcc, s3, v104
	s_mov_b32 s18, s1
	s_nop 0
	v_addc_co_u32_e32 v131, vcc, 0, v105, vcc
	global_load_dwordx4 v[28:31], v[128:129], off offset:-4096
	global_load_dwordx4 v[68:71], v[138:139], off offset:1024
	global_load_dwordx4 v[168:171], v[96:97], off offset:1024
	global_load_dwordx4 v[76:79], v[100:101], off offset:1024
	global_load_dwordx4 v[84:87], v[138:139], off offset:2048
	global_load_dwordx4 v[172:175], v[96:97], off offset:2048
	global_load_dwordx4 v[88:91], v[100:101], off offset:2048
	global_load_dwordx4 v[92:95], v[138:139], off offset:3072
	s_nop 0
	global_load_dwordx4 v[176:179], v[96:97], off offset:3072
	global_load_dwordx4 v[96:99], v[100:101], off offset:3072
	s_nop 0
	global_load_dwordx4 v[100:103], v[140:141], off
	global_load_dwordx4 v[180:183], v[130:131], off
	global_load_dwordx4 v[104:107], v[128:129], off
	global_load_dwordx4 v[108:111], v[142:143], off
	global_load_dwordx4 v[184:187], v[130:131], off offset:1024
	global_load_dwordx4 v[112:115], v[128:129], off offset:1024
	global_load_dwordx4 v[116:119], v[144:145], off
	global_load_dwordx4 v[188:191], v[130:131], off offset:2048
	global_load_dwordx4 v[120:123], v[128:129], off offset:2048
	global_load_dwordx4 v[124:127], v[146:147], off
	global_load_dwordx4 v[192:195], v[130:131], off offset:3072
	s_nop 0
	global_load_dwordx4 v[128:131], v[128:129], off offset:3072
	s_nop 0
	s_waitcnt vmcnt(0)
	v_pk_add_f32 v[166:167], v[166:167], 1.0 op_sel_hi:[1,0]
	v_pk_add_f32 v[164:165], v[164:165], 1.0 op_sel_hi:[1,0]
	v_pk_mul_f32 v[6:7], v[6:7], v[166:167]
	v_pk_mul_f32 v[4:5], v[4:5], v[164:165]
	v_pk_add_f32 v[170:171], v[170:171], 1.0 op_sel_hi:[1,0]
	v_pk_add_f32 v[168:169], v[168:169], 1.0 op_sel_hi:[1,0]
	v_pk_mul_f32 v[70:71], v[70:71], v[170:171]
	v_pk_mul_f32 v[68:69], v[68:69], v[168:169]
	v_pk_add_f32 v[174:175], v[174:175], 1.0 op_sel_hi:[1,0]
	v_pk_add_f32 v[172:173], v[172:173], 1.0 op_sel_hi:[1,0]
	v_pk_mul_f32 v[86:87], v[86:87], v[174:175]
	v_pk_mul_f32 v[84:85], v[84:85], v[172:173]
	v_pk_add_f32 v[178:179], v[178:179], 1.0 op_sel_hi:[1,0]
	v_pk_add_f32 v[176:177], v[176:177], 1.0 op_sel_hi:[1,0]
	v_pk_mul_f32 v[94:95], v[94:95], v[178:179]
	v_pk_mul_f32 v[92:93], v[92:93], v[176:177]
	v_pk_add_f32 v[182:183], v[182:183], 1.0 op_sel_hi:[1,0]
	v_pk_add_f32 v[180:181], v[180:181], 1.0 op_sel_hi:[1,0]
	v_pk_mul_f32 v[102:103], v[102:103], v[182:183]
	v_pk_mul_f32 v[100:101], v[100:101], v[180:181]
	v_pk_add_f32 v[186:187], v[186:187], 1.0 op_sel_hi:[1,0]
	v_pk_add_f32 v[184:185], v[184:185], 1.0 op_sel_hi:[1,0]
	v_pk_mul_f32 v[110:111], v[110:111], v[186:187]
	v_pk_mul_f32 v[108:109], v[108:109], v[184:185]
	v_pk_add_f32 v[190:191], v[190:191], 1.0 op_sel_hi:[1,0]
	v_pk_add_f32 v[188:189], v[188:189], 1.0 op_sel_hi:[1,0]
	v_pk_mul_f32 v[118:119], v[118:119], v[190:191]
	v_pk_mul_f32 v[116:117], v[116:117], v[188:189]
	v_pk_add_f32 v[194:195], v[194:195], 1.0 op_sel_hi:[1,0]
	v_pk_add_f32 v[192:193], v[192:193], 1.0 op_sel_hi:[1,0]
	v_pk_mul_f32 v[126:127], v[126:127], v[194:195]
	v_pk_mul_f32 v[124:125], v[124:125], v[192:193]

; template <bool L16, bool CPY, bool CI>
; __device__ __forceinline__ void norm_rows(Frame& F, const int ra, const int rb, const void* src, const int rbase, const float* g, const float* modl, const int off_sh, const int off_sc, const int nparts) {
;     ...
;         if constexpr (CI) {
;             for (int k = 0; k < nparts; ++k) { const f32x4* pp = (const f32x4*)((const float*)(F.ws + WS_PART) + ((size_t)k * MCTX + (size_t)(m - rbase)) * D) + F.lane;
; #pragma unroll
;                 for (int j = 0; j < 8; ++j) v[j] = v[j] + pp[64 * j]; }
;             f32x4* xw = (f32x4*)((float*)(F.ws + WS_XR) + (size_t)m * D) + F.lane;
; #pragma unroll
;             for (int j = 0; j < 8; ++j) xw[64 * j] = v[j]; }
;         float s = 0.f;
; #pragma unroll
;         for (int j = 0; j < 8; ++j) s += (v[j].x * v[j].x + v[j].y * v[j].y) + (v[j].z * v[j].z + v[j].w * v[j].w);
;         const float r = 1.0f / sqrtf(wave_sum(s) * (1.0f / D) + EPS);
.LBB0_1169:
	global_load_dwordx4 v[164:167], v[150:151], off
	global_load_dwordx4 v[168:171], v[150:151], off offset:1024
	global_load_dwordx4 v[172:175], v[150:151], off offset:2048
	global_load_dwordx4 v[176:179], v[150:151], off offset:3072
	v_add_co_u32_e32 v162, vcc, s33, v150
	s_nop 0
	s_add_i32 s1, s1, -1
	v_addc_co_u32_e32 v163, vcc, 0, v151, vcc
	global_load_dwordx4 v[180:183], v[162:163], off
	global_load_dwordx4 v[184:187], v[162:163], off offset:1024
	global_load_dwordx4 v[188:191], v[162:163], off offset:2048
	global_load_dwordx4 v[192:195], v[162:163], off offset:3072
	s_mov_b64 s[4:5], 0x800000
	v_lshl_add_u64 v[150:151], v[150:151], 0, s[4:5]
	s_cmp_eq_u32 s1, 0
	s_waitcnt vmcnt(0)
	v_pk_add_f32 v[82:83], v[82:83], v[166:167]
	v_pk_add_f32 v[80:81], v[80:81], v[164:165]
	v_pk_add_f32 v[74:75], v[74:75], v[170:171]
	v_pk_add_f32 v[72:73], v[72:73], v[168:169]
	v_pk_add_f32 v[66:67], v[66:67], v[174:175]
	v_pk_add_f32 v[64:65], v[64:65], v[172:173]
	v_pk_add_f32 v[62:63], v[62:63], v[178:179]
	v_pk_add_f32 v[60:61], v[60:61], v[176:177]
	v_pk_add_f32 v[58:59], v[58:59], v[182:183]
	v_pk_add_f32 v[56:57], v[56:57], v[180:181]
	v_pk_add_f32 v[54:55], v[54:55], v[186:187]
	v_pk_add_f32 v[52:53], v[52:53], v[184:185]
	v_pk_add_f32 v[38:39], v[38:39], v[190:191]
	v_pk_add_f32 v[36:37], v[36:37], v[188:189]
	v_pk_add_f32 v[10:11], v[10:11], v[194:195]
	v_pk_add_f32 v[8:9], v[8:9], v[192:193]
	s_cbranch_scc0 .LBB0_1169
	s_ashr_i32 s7, s6, 31
	s_lshl_b64 s[4:5], s[6:7], 13
	v_lshl_add_u64 v[150:151], v[134:135], 0, s[4:5]
	global_store_dwordx4 v[150:151], v[80:83], off
	global_store_dwordx4 v[150:151], v[72:75], off offset:1024
	global_store_dwordx4 v[150:151], v[64:67], off offset:2048
	global_store_dwordx4 v[150:151], v[60:63], off offset:3072
	v_add_co_u32_e32 v150, vcc, s33, v150
	v_mov_b32_e32 v158, v81
	s_nop 0
	v_addc_co_u32_e32 v151, vcc, 0, v151, vcc
	v_mov_b32_e32 v159, v73
	global_store_dwordx4 v[150:151], v[56:59], off
	global_store_dwordx4 v[150:151], v[52:55], off offset:1024
	global_store_dwordx4 v[150:151], v[36:39], off offset:2048
	global_store_dwordx4 v[150:151], v[8:11], off offset:3072
	v_mov_b32_e32 v150, v80
	v_mov_b32_e32 v151, v72
	v_pk_mul_f32 v[158:159], v[158:159], v[158:159]
	v_mov_b32_e32 v160, v83
	v_mov_b32_e32 v161, v75
	v_pk_fma_f32 v[150:151], v[150:151], v[150:151], v[158:159]
	v_mov_b32_e32 v158, v82
	v_mov_b32_e32 v159, v74
	v_pk_mul_f32 v[160:161], v[160:161], v[160:161]
	s_mov_b32 s3, 0xf800000
	v_pk_fma_f32 v[158:159], v[158:159], v[158:159], v[160:161]
	v_pk_mul_f32 v[160:161], v[64:65], v[64:65]
	v_pk_add_f32 v[150:151], v[150:151], v[158:159]
	v_pk_mul_f32 v[158:159], v[66:67], v[66:67]
	v_pk_add_f32 v[150:151], v[150:151], v[150:151] op_sel:[0,1] op_sel_hi:[1,0]
	v_pk_mov_b32 v[162:163], v[160:161], v[158:159] op_sel:[1,0]
	v_mov_b32_e32 v161, v159
	v_pk_add_f32 v[158:159], v[162:163], v[160:161]
	v_mul_f32_e32 v160, v56, v56
	v_mul_f32_e32 v161, v57, v57
	v_pk_add_f32 v[158:159], v[158:159], v[158:159] op_sel:[0,1] op_sel_hi:[1,0]
	v_mov_b32_e32 v151, v160
	v_mov_b32_e32 v159, v161
	v_pk_add_f32 v[150:151], v[150:151], v[158:159]
	v_mul_f32_e32 v158, v61, v61
	v_mul_f32_e32 v160, v63, v63
	v_mul_f32_e32 v162, v58, v58
	v_mul_f32_e32 v163, v59, v59
	v_pk_fma_f32 v[158:159], v[60:61], v[60:61], v[158:159] op_sel_hi:[1,1,0]
	v_pk_fma_f32 v[160:161], v[62:63], v[62:63], v[160:161] op_sel_hi:[1,1,0]
	v_mov_b32_e32 v159, v162
	v_mov_b32_e32 v161, v163
	v_pk_add_f32 v[158:159], v[158:159], v[160:161]
	v_pk_mul_f32 v[160:161], v[52:53], v[52:53]
	v_pk_add_f32 v[150:151], v[150:151], v[158:159]
	v_pk_mul_f32 v[158:159], v[54:55], v[54:55]
	v_pk_add_f32 v[150:151], v[150:151], v[150:151] op_sel:[0,1] op_sel_hi:[1,0]
	v_pk_mov_b32 v[162:163], v[160:161], v[158:159] op_sel:[1,0]
	v_mov_b32_e32 v161, v159
	v_pk_add_f32 v[158:159], v[162:163], v[160:161]
	v_mul_f32_e32 v160, v8, v8
	v_mul_f32_e32 v161, v9, v9
	v_pk_add_f32 v[158:159], v[158:159], v[158:159] op_sel:[0,1] op_sel_hi:[1,0]
	v_mov_b32_e32 v151, v160
	v_mov_b32_e32 v159, v161
	v_pk_add_f32 v[150:151], v[150:151], v[158:159]
	v_mul_f32_e32 v158, v37, v37
	v_mul_f32_e32 v160, v39, v39
	v_mul_f32_e32 v162, v10, v10
	v_mul_f32_e32 v163, v11, v11
	v_pk_fma_f32 v[158:159], v[36:37], v[36:37], v[158:159] op_sel_hi:[1,1,0]
	v_pk_fma_f32 v[160:161], v[38:39], v[38:39], v[160:161] op_sel_hi:[1,1,0]
	v_mov_b32_e32 v159, v162
	v_mov_b32_e32 v161, v163
	v_pk_add_f32 v[158:159], v[158:159], v[160:161]
	s_add_i32 s1, s6, 1
	v_pk_add_f32 v[150:151], v[150:151], v[158:159]
	s_add_i32 s0, s0, 1
	v_add_f32_e32 v150, v150, v151
	ds_bpermute_b32 v151, v152, v150
	s_waitcnt lgkmcnt(0)
	v_add_f32_e32 v150, v150, v151
	ds_bpermute_b32 v151, v153, v150
	s_waitcnt lgkmcnt(0)
	v_add_f32_e32 v150, v150, v151
	ds_bpermute_b32 v151, v154, v150
	s_waitcnt lgkmcnt(0)
	v_add_f32_e32 v150, v150, v151
	ds_bpermute_b32 v151, v155, v150
	s_waitcnt lgkmcnt(0)
	v_add_f32_e32 v150, v150, v151
	ds_bpermute_b32 v151, v156, v150
	s_waitcnt lgkmcnt(0)
; __device__ __forceinline__ unsigned pk_h2(float lo, float hi) { f16x2 p; p.x = (_Float16)__builtin_amdgcn_fmed3f(lo, -65504.0f, 65504.0f); p.y = (_Float16)__builtin_amdgcn_fmed3f(hi, -65504.0f, 65504.0f); return __builtin_bit_cast(unsigned, p); }
; __device__ __forceinline__ unsigned pk2h(float lo, float hi) { return pg8::cvt_pk_bf16(lo, hi); }
; template <bool L16, bool CPY, bool CI>
; __device__ __forceinline__ void norm_rows(Frame& F, const int ra, const int rb, const void* src, const int rbase, const float* g, const float* modl, const int off_sh, const int off_sc, const int nparts) {
;     ...
;         const float r = 1.0f / sqrtf(wave_sum(s) * (1.0f / D) + EPS);
;         v2u* o8 = (v2u*)(H + (size_t)m * D) + F.lane;
; #pragma unroll
;         for (int j = 0; j < 8; ++j) { const f32x4 y = v[j] * r * gm[j] + sh[j]; v2u ww; ww.x = pk2h(y.x, y.y); ww.y = pk2h(y.z, y.w); o8[64 * j] = ww; }
;         if constexpr (CPY) { v2u* c8 = (v2u*)((bf16*)(F.ws + WS_X16) + (size_t)m * D) + F.lane;
; #pragma unroll
;             for (int j = 0; j < 8; ++j) { v2u ww; ww.x = pg8::pk_h2(v[j].x, v[j].y); ww.y = pg8::pk_h2(v[j].z, v[j].w); c8[64 * j] = ww; } }
;         if constexpr (L16) {
; #pragma unroll
;             for (int j = 0; j < 8; ++j) hv[j] = hw[j];
;         } else {
; #pragma unroll
;             for (int j = 0; j < 8; ++j) v[j] = w[j]; }
	v_add_f32_e32 v150, v150, v151
	ds_bpermute_b32 v151, v157, v150
	s_waitcnt lgkmcnt(0)
	v_add_f32_e32 v150, v150, v151
	v_fmamk_f32 v150, v150, 0x3a000000, v244
	v_cmp_gt_f32_e32 vcc, s3, v150
	v_mul_f32_e32 v151, 0x4f800000, v150
	s_nop 0
	v_cndmask_b32_e32 v150, v150, v151, vcc
	v_sqrt_f32_e32 v151, v150
	s_nop 0
	v_add_u32_e32 v158, -1, v151
	v_fma_f32 v159, -v158, v151, v150
	v_cmp_ge_f32_e64 s[4:5], 0, v159
	v_add_u32_e32 v159, 1, v151
	s_nop 0
	v_cndmask_b32_e64 v158, v151, v158, s[4:5]
	v_fma_f32 v151, -v159, v151, v150
	v_cmp_lt_f32_e64 s[4:5], 0, v151
	s_nop 1
	v_cndmask_b32_e64 v151, v158, v159, s[4:5]
	v_mul_f32_e32 v158, 0x37800000, v151
	v_cndmask_b32_e32 v151, v151, v158, vcc
	v_cmp_class_f32_e32 vcc, v150, v245
	s_nop 1
	v_cndmask_b32_e32 v150, v151, v150, vcc
	v_div_scale_f32 v151, s[4:5], v150, v150, 1.0
	v_rcp_f32_e32 v158, v151
	s_lshl_b64 s[4:5], s[6:7], 12
	s_mov_b32 s6, s1
	v_fma_f32 v159, -v151, v158, 1.0
	v_fmac_f32_e32 v158, v159, v158
	v_div_scale_f32 v159, vcc, 1.0, v150, 1.0
	v_mul_f32_e32 v160, v159, v158
	v_fma_f32 v161, -v151, v160, v159
	v_fmac_f32_e32 v160, v161, v158
	v_fma_f32 v151, -v151, v160, v159
	v_div_fmas_f32 v151, v151, v158, v160
	v_div_fixup_f32 v150, v151, v150, 1.0
	v_pk_mul_f32 v[80:81], v[80:81], v[150:151] op_sel_hi:[1,0]
	v_pk_mul_f32 v[72:73], v[72:73], v[150:151] op_sel_hi:[1,0]
	v_pk_mul_f32 v[64:65], v[64:65], v[150:151] op_sel_hi:[1,0]
	v_pk_mul_f32 v[60:61], v[60:61], v[150:151] op_sel_hi:[1,0]
	v_pk_mul_f32 v[56:57], v[56:57], v[150:151] op_sel_hi:[1,0]
	v_pk_mul_f32 v[52:53], v[52:53], v[150:151] op_sel_hi:[1,0]
	v_pk_mul_f32 v[36:37], v[36:37], v[150:151] op_sel_hi:[1,0]
	v_pk_mul_f32 v[8:9], v[8:9], v[150:151] op_sel_hi:[1,0]
	v_lshl_add_u64 v[158:159], v[136:137], 0, s[4:5]
	v_pk_mul_f32 v[82:83], v[82:83], v[150:151] op_sel_hi:[1,0]
	v_pk_fma_f32 v[80:81], v[4:5], v[80:81], v[28:29]
	v_pk_mul_f32 v[74:75], v[74:75], v[150:151] op_sel_hi:[1,0]
	v_pk_fma_f32 v[72:73], v[68:69], v[72:73], v[76:77]
	v_pk_mul_f32 v[66:67], v[66:67], v[150:151] op_sel_hi:[1,0]
	v_pk_fma_f32 v[64:65], v[84:85], v[64:65], v[88:89]
	v_pk_mul_f32 v[62:63], v[62:63], v[150:151] op_sel_hi:[1,0]
	v_pk_fma_f32 v[60:61], v[92:93], v[60:61], v[96:97]
	v_pk_mul_f32 v[58:59], v[58:59], v[150:151] op_sel_hi:[1,0]
	v_pk_fma_f32 v[56:57], v[100:101], v[56:57], v[104:105]
	v_pk_mul_f32 v[54:55], v[54:55], v[150:151] op_sel_hi:[1,0]
	v_pk_fma_f32 v[52:53], v[108:109], v[52:53], v[112:113]
	v_pk_mul_f32 v[38:39], v[38:39], v[150:151] op_sel_hi:[1,0]
	v_pk_fma_f32 v[36:37], v[116:117], v[36:37], v[120:121]
	v_pk_mul_f32 v[10:11], v[10:11], v[150:151] op_sel_hi:[1,0]
	v_pk_fma_f32 v[8:9], v[124:125], v[8:9], v[128:129]
	v_pk_fma_f32 v[82:83], v[6:7], v[82:83], v[30:31]
	v_cvt_pk_bf16_f32 v80, v80, v81
	v_pk_fma_f32 v[74:75], v[70:71], v[74:75], v[78:79]
	v_cvt_pk_bf16_f32 v81, v82, v83
	global_store_dwordx2 v[158:159], v[80:81], off
	v_cvt_pk_bf16_f32 v72, v72, v73
	v_cvt_pk_bf16_f32 v73, v74, v75
	global_store_dwordx2 v[158:159], v[72:73], off offset:512
	v_pk_fma_f32 v[66:67], v[86:87], v[66:67], v[90:91]
	v_cvt_pk_bf16_f32 v64, v64, v65
	v_pk_fma_f32 v[62:63], v[94:95], v[62:63], v[98:99]
	v_cvt_pk_bf16_f32 v65, v66, v67
	global_store_dwordx2 v[158:159], v[64:65], off offset:1024
	v_cvt_pk_bf16_f32 v60, v60, v61
	v_cvt_pk_bf16_f32 v61, v62, v63
	global_store_dwordx2 v[158:159], v[60:61], off offset:1536
	v_pk_fma_f32 v[58:59], v[102:103], v[58:59], v[106:107]
	v_cvt_pk_bf16_f32 v56, v56, v57
	v_pk_fma_f32 v[54:55], v[110:111], v[54:55], v[114:115]
	v_cvt_pk_bf16_f32 v57, v58, v59
	global_store_dwordx2 v[158:159], v[56:57], off offset:2048
	v_cvt_pk_bf16_f32 v52, v52, v53
	v_cvt_pk_bf16_f32 v53, v54, v55
	global_store_dwordx2 v[158:159], v[52:53], off offset:2560
	v_pk_fma_f32 v[38:39], v[118:119], v[38:39], v[122:123]
	v_cvt_pk_bf16_f32 v36, v36, v37
	v_pk_fma_f32 v[10:11], v[126:127], v[10:11], v[130:131]
	v_cvt_pk_bf16_f32 v37, v38, v39
	global_store_dwordx2 v[158:159], v[36:37], off offset:3072
	v_cvt_pk_bf16_f32 v8, v8, v9
	v_cvt_pk_bf16_f32 v9, v10, v11
	global_store_dwordx2 v[158:159], v[8:9], off offset:3584
	s_and_b64 vcc, exec, s[10:11]
	v_mov_b32_e32 v80, v24
	v_mov_b32_e32 v81, v25
	v_mov_b32_e32 v82, v26
	v_mov_b32_e32 v83, v27
	v_mov_b32_e32 v72, v16
	v_mov_b32_e32 v73, v17
	v_mov_b32_e32 v74, v18
	v_mov_b32_e32 v75, v19
	v_mov_b32_e32 v64, v12
	v_mov_b32_e32 v65, v13
	v_mov_b32_e32 v66, v14
	v_mov_b32_e32 v67, v15
	v_mov_b32_e32 v60, v20
	v_mov_b32_e32 v61, v21
	v_mov_b32_e32 v62, v22
	v_mov_b32_e32 v63, v23
	v_mov_b32_e32 v56, v32
	v_mov_b32_e32 v57, v33
	v_mov_b32_e32 v58, v34
	v_mov_b32_e32 v59, v35
	v_mov_b32_e32 v52, v48
	v_mov_b32_e32 v53, v49
	v_mov_b32_e32 v54, v50
	v_mov_b32_e32 v55, v51
	v_mov_b32_e32 v36, v44
	v_mov_b32_e32 v37, v45
	v_mov_b32_e32 v38, v46
	v_mov_b32_e32 v39, v47
	v_mov_b32_e32 v8, v40
	v_mov_b32_e32 v9, v41
	v_mov_b32_e32 v10, v42
	v_mov_b32_e32 v11, v43
	s_cbranch_vccz .LBB0_1164
